# gMLP queue: first index requested in the epilogue of the workgroup's last attention item (hides one atomic round trip)
# speedup vs baseline: 1.0017x; 1.0017x over previous
.Lattn_end4:
	s_andn2_b64 vcc, exec, s[26:27]
	s_cbranch_vccnz .Lgq_skip
	s_load_dwordx2 s[62:63], s[0:1], 0xe0
	s_waitcnt lgkmcnt(0)
	s_add_u32 s62, s62, 0x3600
	s_addc_u32 s63, s63, 0
	s_and_saveexec_b64 s[64:65], s[44:45]
	s_cbranch_execz .Lgq_rest
	v_mov_b32_e32 v253, 0
	v_mov_b32_e32 v252, 1
	global_atomic_add v252, v253, v252, s[62:63] sc0
.Lgq_rest:
	s_mov_b64 exec, s[64:65]

.Lgq_entry:
	s_load_dwordx2 s[4:5], s[0:1], 0xe0
	s_waitcnt lgkmcnt(0)
	s_add_u32 s8, s4, 0x3600
	s_addc_u32 s9, s5, 0
	s_and_saveexec_b64 s[4:5], s[44:45]
	s_cbranch_execz .LBB0_379
	v_readfirstlane_b32 s3, v252
	v_mov_b32_e32 v2, 0
	s_nop 0
	v_mov_b32_e32 v1, s3
	ds_write_b32 v2, v1 offset:8
	s_branch .LBB0_379
